# sixth group barrier: final-norm rows re-dealt to the workgroup's own group so the seam 16-17 is a 32-workgroup barrier too
# baseline (speedup 1.0000x reference)
.LBB0_2757:
	s_cmp_gt_i32 s87, 17
	s_cselect_b64 s[0:1], -1, 0
	s_and_b64 s[2:3], s[6:7], s[0:1]
	s_andn2_b64 vcc, exec, s[2:3]
	s_cbranch_vccnz .LBB0_2811
	s_waitcnt vmcnt(0)
	s_waitcnt vmcnt(0)
	s_barrier
	s_mov_b64 s[2:3], exec
	v_readlane_b32 s4, v251, 1
	v_readlane_b32 s5, v251, 2
	s_and_b64 s[4:5], s[2:3], s[4:5]
	s_mov_b64 exec, s[4:5]
	s_cbranch_execz .LBB0_2810
	s_waitcnt vmcnt(0) expcnt(0) lgkmcnt(0)
	buffer_inv sc1
	s_and_b32 s4, s90, 7
	s_lshl_b32 s4, s4, 8
	s_add_i32 s4, s4, 0x3600
	v_mov_b32_e32 v0, s4
	v_mov_b32_e32 v2, 1
	global_atomic_add v0, v0, v2, s[96:97] sc0
	s_nop 0
	v_mov_b32_e32 v2, 0x3e00
	global_load_dword v2, v2, s[96:97] sc1
	s_waitcnt vmcnt(0)
	v_readfirstlane_b32 s5, v2
	v_readfirstlane_b32 vcc_lo, v0
	s_cmp_lg_u32 s5, 0
	s_cbranch_scc1 .Lgb_orig5
	s_or_b32 s5, vcc_lo, 31
	s_cmp_eq_u32 s5, vcc_lo
	s_cbranch_scc1 .Lgb_done5
	s_add_i32 s5, s5, 1
	s_mov_b32 vcc_hi, 0
	v_mov_b32_e32 v0, s4

.LBB0_2811:
	s_cmp_lt_i32 s86, 18
	s_cselect_b64 s[2:3], -1, 0
	s_and_b64 s[0:1], s[2:3], s[0:1]
	s_andn2_b64 vcc, exec, s[0:1]
	s_cbranch_vccnz .LBB0_2815
	s_cmpk_gt_i32 s88, 0x7fff
	s_cbranch_scc1 .LBB0_2815
	s_and_b32 s28, s90, 7
	s_lshr_b32 s29, s90, 3
	v_readlane_b32 s30, v251, 7
	s_lshl_b32 s31, s28, 12
	s_lshl_b32 s29, s29, 3
	s_add_i32 s88, s31, s29
	s_add_i32 s88, s88, s30
	s_add_i32 s28, s31, 0x1000
	s_movk_i32 s94, 0x100
	v_lshlrev_b32_e32 v16, 4, v152
	global_load_dwordx4 v[0:3], v16, s[72:73]
	global_load_dwordx4 v[4:7], v16, s[72:73] offset:1024
	global_load_dwordx4 v[8:11], v16, s[72:73] offset:2048
	global_load_dwordx4 v[12:15], v16, s[72:73] offset:3072
	s_ashr_i32 s89, s88, 31
	s_ashr_i32 s95, s94, 31
	s_lshl_b64 s[6:7], s[88:89], 11
	s_lshl_b64 s[0:1], s[88:89], 6
	s_lshl_b64 s[4:5], s[94:95], 6
	v_lshl_or_b32 v18, v152, 3, s6
	v_mov_b32_e32 v19, s7
	s_lshl_b64 s[6:7], s[94:95], 11
	s_lshl_b64 s[8:9], s[88:89], 12
	s_add_u32 s8, s74, s8
	v_mov_b32_e32 v17, 0
	s_addc_u32 s9, s75, s9
	v_lshl_add_u64 v[20:21], s[8:9], 0, v[16:17]
	s_mov_b64 s[8:9], 0xc00
	v_lshl_add_u64 v[20:21], v[20:21], 0, s[8:9]
	s_lshl_b64 s[8:9], s[94:95], 12
	v_mov_b32_e32 v16, 0x1fd00000
	v_mov_b32_e32 v22, 0x358637bd
	s_mov_b32 s10, 0x800000
	v_lshl_add_u64 v[18:19], s[96:97], 0, v[18:19]
	s_mov_b32 s20, 0x3000000
	s_mov_b32 s21, 0
	v_lshl_add_u64 v[18:19], v[18:19], 0, s[20:21]
	s_add_u32 s12, s96, s0
	s_addc_u32 s13, s97, s1
	s_add_u32 s12, s12, 0x1fd00000
	s_addc_u32 s13, s13, 0
	s_mov_b32 s22, s88
	global_load_dwordx2 v[56:57], v[18:19], off
	global_load_dwordx2 v[58:59], v[18:19], off offset:512
	global_load_dwordx2 v[60:61], v[18:19], off offset:1024
	global_load_dwordx2 v[62:63], v[18:19], off offset:1536
	global_load_dwordx4 v[64:67], v17, s[12:13] offset:48
	global_load_dwordx4 v[68:71], v17, s[12:13] offset:32
	global_load_dwordx4 v[72:75], v17, s[12:13] offset:16
	global_load_dwordx4 v[76:79], v17, s[12:13]
	s_add_i32 s22, s22, s94
	s_cmp_lt_i32 s22, s28
	s_cselect_b32 s24, s6, 0
	s_cselect_b32 s25, s7, 0
	s_cselect_b32 s26, s4, 0
	s_cselect_b32 s27, s5, 0
	v_lshl_add_u64 v[18:19], v[18:19], 0, s[24:25]
	s_add_u32 s12, s12, s26
	s_addc_u32 s13, s13, s27
	global_load_dwordx2 v[80:81], v[18:19], off
	global_load_dwordx2 v[82:83], v[18:19], off offset:512
	global_load_dwordx2 v[84:85], v[18:19], off offset:1024
	global_load_dwordx2 v[86:87], v[18:19], off offset:1536
	global_load_dwordx4 v[88:91], v17, s[12:13] offset:48
	global_load_dwordx4 v[92:95], v17, s[12:13] offset:32
	global_load_dwordx4 v[96:99], v17, s[12:13] offset:16
	global_load_dwordx4 v[100:103], v17, s[12:13]
	s_add_i32 s22, s22, s94
	s_cmp_lt_i32 s22, s28
	s_cselect_b32 s24, s6, 0
	s_cselect_b32 s25, s7, 0
	s_cselect_b32 s26, s4, 0
	s_cselect_b32 s27, s5, 0
	v_lshl_add_u64 v[18:19], v[18:19], 0, s[24:25]
	s_add_u32 s12, s12, s26
	s_addc_u32 s13, s13, s27
	global_load_dwordx2 v[104:105], v[18:19], off
	global_load_dwordx2 v[106:107], v[18:19], off offset:512
	global_load_dwordx2 v[108:109], v[18:19], off offset:1024
	global_load_dwordx2 v[110:111], v[18:19], off offset:1536
	global_load_dwordx4 v[112:115], v17, s[12:13] offset:48
	global_load_dwordx4 v[116:119], v17, s[12:13] offset:32
	global_load_dwordx4 v[120:123], v17, s[12:13] offset:16
	global_load_dwordx4 v[124:127], v17, s[12:13]
	s_add_i32 s22, s22, s94
	s_cmp_lt_i32 s22, s28
	s_cselect_b32 s24, s6, 0
	s_cselect_b32 s25, s7, 0
	s_cselect_b32 s26, s4, 0
	s_cselect_b32 s27, s5, 0
	v_lshl_add_u64 v[18:19], v[18:19], 0, s[24:25]
	s_add_u32 s12, s12, s26
	s_addc_u32 s13, s13, s27
	s_waitcnt vmcnt(16)
	v_pk_add_f32 v[74:75], v[78:79], v[74:75]
	v_pk_add_f32 v[72:73], v[76:77], v[72:73]
	v_pk_add_f32 v[70:71], v[74:75], v[70:71]
	v_pk_add_f32 v[68:69], v[72:73], v[68:69]
	v_pk_add_f32 v[66:67], v[70:71], v[66:67]
	v_pk_add_f32 v[64:65], v[68:69], v[64:65]
	v_mov_b32_e32 v69, v66
	v_mov_b32_e32 v68, v65
	v_mov_b32_e32 v65, v67
	v_pk_add_f32 v[64:65], v[68:69], v[64:65]
	v_lshlrev_b32_e32 v128, 16, v56
	v_and_b32_e32 v129, 0xffff0000, v56
	v_lshlrev_b32_e32 v132, 16, v58
	v_and_b32_e32 v133, 0xffff0000, v58
	v_lshlrev_b32_e32 v136, 16, v60
	v_and_b32_e32 v137, 0xffff0000, v60
	v_lshlrev_b32_e32 v140, 16, v62
	v_and_b32_e32 v141, 0xffff0000, v62
	v_add_f32_e32 v23, v64, v65
	v_fmamk_f32 v23, v23, 0x3a800000, v22
	v_mul_f32_e32 v50, 0x4b800000, v23
	v_cmp_gt_f32_e32 vcc, s10, v23
	v_lshlrev_b32_e32 v130, 16, v57
	v_and_b32_e32 v131, 0xffff0000, v57
	v_lshlrev_b32_e32 v134, 16, v59
	v_and_b32_e32 v135, 0xffff0000, v59
	v_cndmask_b32_e32 v23, v23, v50, vcc
	v_rsq_f32_e32 v23, v23
	v_lshlrev_b32_e32 v138, 16, v61
	v_and_b32_e32 v139, 0xffff0000, v61
	v_lshlrev_b32_e32 v142, 16, v63
	v_and_b32_e32 v143, 0xffff0000, v63
	v_mul_f32_e32 v50, 0x45800000, v23
	s_nop 1
	v_cndmask_b32_e32 v50, v23, v50, vcc
	v_pk_mul_f32 v[24:25], v[50:51], v[128:129] op_sel_hi:[0,1]
	v_pk_mul_f32 v[26:27], v[50:51], v[130:131] op_sel_hi:[0,1]
	v_pk_mul_f32 v[28:29], v[50:51], v[132:133] op_sel_hi:[0,1]
	v_pk_mul_f32 v[30:31], v[50:51], v[134:135] op_sel_hi:[0,1]
	v_pk_mul_f32 v[32:33], v[50:51], v[136:137] op_sel_hi:[0,1]
	v_pk_mul_f32 v[34:35], v[50:51], v[138:139] op_sel_hi:[0,1]
	v_pk_mul_f32 v[36:37], v[50:51], v[140:141] op_sel_hi:[0,1]
	v_pk_mul_f32 v[38:39], v[50:51], v[142:143] op_sel_hi:[0,1]
	v_pk_mul_f32 v[24:25], v[0:1], v[24:25]
	v_pk_mul_f32 v[26:27], v[2:3], v[26:27]
	v_pk_mul_f32 v[28:29], v[4:5], v[28:29]
	v_pk_mul_f32 v[30:31], v[6:7], v[30:31]
	v_pk_mul_f32 v[32:33], v[8:9], v[32:33]
	v_pk_mul_f32 v[34:35], v[10:11], v[34:35]
	v_pk_mul_f32 v[36:37], v[12:13], v[36:37]
	v_pk_mul_f32 v[38:39], v[14:15], v[38:39]
	global_store_dwordx4 v[20:21], v[24:27], off offset:-3072
	global_store_dwordx4 v[20:21], v[28:31], off offset:-2048
	global_store_dwordx4 v[20:21], v[32:35], off offset:-1024
	global_store_dwordx4 v[20:21], v[36:39], off
	v_lshl_add_u64 v[20:21], v[20:21], 0, s[8:9]
	s_add_i32 s88, s88, s94
	s_cmp_lt_i32 s88, s28
	s_cbranch_scc0 .Lfn_done
.Lfn_loop:
	global_load_dwordx2 v[56:57], v[18:19], off
	global_load_dwordx2 v[58:59], v[18:19], off offset:512
	global_load_dwordx2 v[60:61], v[18:19], off offset:1024
	global_load_dwordx2 v[62:63], v[18:19], off offset:1536
	global_load_dwordx4 v[64:67], v17, s[12:13] offset:48
	global_load_dwordx4 v[68:71], v17, s[12:13] offset:32
	global_load_dwordx4 v[72:75], v17, s[12:13] offset:16
	global_load_dwordx4 v[76:79], v17, s[12:13]
	s_add_i32 s22, s22, s94
	s_cmp_lt_i32 s22, s28
	s_cselect_b32 s24, s6, 0
	s_cselect_b32 s25, s7, 0
	s_cselect_b32 s26, s4, 0
	s_cselect_b32 s27, s5, 0
	v_lshl_add_u64 v[18:19], v[18:19], 0, s[24:25]
	s_add_u32 s12, s12, s26
	s_addc_u32 s13, s13, s27
	s_waitcnt vmcnt(20)
	v_pk_add_f32 v[98:99], v[102:103], v[98:99]
	v_pk_add_f32 v[96:97], v[100:101], v[96:97]
	v_pk_add_f32 v[94:95], v[98:99], v[94:95]
	v_pk_add_f32 v[92:93], v[96:97], v[92:93]
	v_pk_add_f32 v[90:91], v[94:95], v[90:91]
	v_pk_add_f32 v[88:89], v[92:93], v[88:89]
	v_mov_b32_e32 v93, v90
	v_mov_b32_e32 v92, v89
	v_mov_b32_e32 v89, v91
	v_pk_add_f32 v[88:89], v[92:93], v[88:89]
	v_lshlrev_b32_e32 v128, 16, v80
	v_and_b32_e32 v129, 0xffff0000, v80
	v_lshlrev_b32_e32 v132, 16, v82
	v_and_b32_e32 v133, 0xffff0000, v82
	v_lshlrev_b32_e32 v136, 16, v84
	v_and_b32_e32 v137, 0xffff0000, v84
	v_lshlrev_b32_e32 v140, 16, v86
	v_and_b32_e32 v141, 0xffff0000, v86
	v_add_f32_e32 v23, v88, v89
	v_fmamk_f32 v23, v23, 0x3a800000, v22
	v_mul_f32_e32 v50, 0x4b800000, v23
	v_cmp_gt_f32_e32 vcc, s10, v23
	v_lshlrev_b32_e32 v130, 16, v81
	v_and_b32_e32 v131, 0xffff0000, v81
	v_lshlrev_b32_e32 v134, 16, v83
	v_and_b32_e32 v135, 0xffff0000, v83
	v_cndmask_b32_e32 v23, v23, v50, vcc
	v_rsq_f32_e32 v23, v23
	v_lshlrev_b32_e32 v138, 16, v85
	v_and_b32_e32 v139, 0xffff0000, v85
	v_lshlrev_b32_e32 v142, 16, v87
	v_and_b32_e32 v143, 0xffff0000, v87
	v_mul_f32_e32 v50, 0x45800000, v23
	s_nop 1
	v_cndmask_b32_e32 v50, v23, v50, vcc
	v_pk_mul_f32 v[24:25], v[50:51], v[128:129] op_sel_hi:[0,1]
	v_pk_mul_f32 v[26:27], v[50:51], v[130:131] op_sel_hi:[0,1]
	v_pk_mul_f32 v[28:29], v[50:51], v[132:133] op_sel_hi:[0,1]
	v_pk_mul_f32 v[30:31], v[50:51], v[134:135] op_sel_hi:[0,1]
	v_pk_mul_f32 v[32:33], v[50:51], v[136:137] op_sel_hi:[0,1]
	v_pk_mul_f32 v[34:35], v[50:51], v[138:139] op_sel_hi:[0,1]
	v_pk_mul_f32 v[36:37], v[50:51], v[140:141] op_sel_hi:[0,1]
	v_pk_mul_f32 v[38:39], v[50:51], v[142:143] op_sel_hi:[0,1]
	v_pk_mul_f32 v[24:25], v[0:1], v[24:25]
	v_pk_mul_f32 v[26:27], v[2:3], v[26:27]
	v_pk_mul_f32 v[28:29], v[4:5], v[28:29]
	v_pk_mul_f32 v[30:31], v[6:7], v[30:31]
	v_pk_mul_f32 v[32:33], v[8:9], v[32:33]
	v_pk_mul_f32 v[34:35], v[10:11], v[34:35]
	v_pk_mul_f32 v[36:37], v[12:13], v[36:37]
	v_pk_mul_f32 v[38:39], v[14:15], v[38:39]
	global_store_dwordx4 v[20:21], v[24:27], off offset:-3072
	global_store_dwordx4 v[20:21], v[28:31], off offset:-2048
	global_store_dwordx4 v[20:21], v[32:35], off offset:-1024
	global_store_dwordx4 v[20:21], v[36:39], off
	v_lshl_add_u64 v[20:21], v[20:21], 0, s[8:9]
	s_add_i32 s88, s88, s94
	s_cmp_lt_i32 s88, s28
	s_cbranch_scc0 .Lfn_done
	global_load_dwordx2 v[80:81], v[18:19], off
	global_load_dwordx2 v[82:83], v[18:19], off offset:512
	global_load_dwordx2 v[84:85], v[18:19], off offset:1024
	global_load_dwordx2 v[86:87], v[18:19], off offset:1536
	global_load_dwordx4 v[88:91], v17, s[12:13] offset:48
	global_load_dwordx4 v[92:95], v17, s[12:13] offset:32
	global_load_dwordx4 v[96:99], v17, s[12:13] offset:16
	global_load_dwordx4 v[100:103], v17, s[12:13]
	s_add_i32 s22, s22, s94
	s_cmp_lt_i32 s22, s28
	s_cselect_b32 s24, s6, 0
	s_cselect_b32 s25, s7, 0
	s_cselect_b32 s26, s4, 0
	s_cselect_b32 s27, s5, 0
	v_lshl_add_u64 v[18:19], v[18:19], 0, s[24:25]
	s_add_u32 s12, s12, s26
	s_addc_u32 s13, s13, s27
	s_waitcnt vmcnt(20)
	v_pk_add_f32 v[122:123], v[126:127], v[122:123]
	v_pk_add_f32 v[120:121], v[124:125], v[120:121]
	v_pk_add_f32 v[118:119], v[122:123], v[118:119]
	v_pk_add_f32 v[116:117], v[120:121], v[116:117]
	v_pk_add_f32 v[114:115], v[118:119], v[114:115]
	v_pk_add_f32 v[112:113], v[116:117], v[112:113]
	v_mov_b32_e32 v117, v114
	v_mov_b32_e32 v116, v113
	v_mov_b32_e32 v113, v115
	v_pk_add_f32 v[112:113], v[116:117], v[112:113]
	v_lshlrev_b32_e32 v128, 16, v104
	v_and_b32_e32 v129, 0xffff0000, v104
	v_lshlrev_b32_e32 v132, 16, v106
	v_and_b32_e32 v133, 0xffff0000, v106
	v_lshlrev_b32_e32 v136, 16, v108
	v_and_b32_e32 v137, 0xffff0000, v108
	v_lshlrev_b32_e32 v140, 16, v110
	v_and_b32_e32 v141, 0xffff0000, v110
	v_add_f32_e32 v23, v112, v113
	v_fmamk_f32 v23, v23, 0x3a800000, v22
	v_mul_f32_e32 v50, 0x4b800000, v23
	v_cmp_gt_f32_e32 vcc, s10, v23
	v_lshlrev_b32_e32 v130, 16, v105
	v_and_b32_e32 v131, 0xffff0000, v105
	v_lshlrev_b32_e32 v134, 16, v107
	v_and_b32_e32 v135, 0xffff0000, v107
	v_cndmask_b32_e32 v23, v23, v50, vcc
	v_rsq_f32_e32 v23, v23
	v_lshlrev_b32_e32 v138, 16, v109
	v_and_b32_e32 v139, 0xffff0000, v109
	v_lshlrev_b32_e32 v142, 16, v111
	v_and_b32_e32 v143, 0xffff0000, v111
	v_mul_f32_e32 v50, 0x45800000, v23
	s_nop 1
	v_cndmask_b32_e32 v50, v23, v50, vcc
	v_pk_mul_f32 v[24:25], v[50:51], v[128:129] op_sel_hi:[0,1]
	v_pk_mul_f32 v[26:27], v[50:51], v[130:131] op_sel_hi:[0,1]
	v_pk_mul_f32 v[28:29], v[50:51], v[132:133] op_sel_hi:[0,1]
	v_pk_mul_f32 v[30:31], v[50:51], v[134:135] op_sel_hi:[0,1]
	v_pk_mul_f32 v[32:33], v[50:51], v[136:137] op_sel_hi:[0,1]
	v_pk_mul_f32 v[34:35], v[50:51], v[138:139] op_sel_hi:[0,1]
	v_pk_mul_f32 v[36:37], v[50:51], v[140:141] op_sel_hi:[0,1]
	v_pk_mul_f32 v[38:39], v[50:51], v[142:143] op_sel_hi:[0,1]
	v_pk_mul_f32 v[24:25], v[0:1], v[24:25]
	v_pk_mul_f32 v[26:27], v[2:3], v[26:27]
	v_pk_mul_f32 v[28:29], v[4:5], v[28:29]
	v_pk_mul_f32 v[30:31], v[6:7], v[30:31]
	v_pk_mul_f32 v[32:33], v[8:9], v[32:33]
	v_pk_mul_f32 v[34:35], v[10:11], v[34:35]
	v_pk_mul_f32 v[36:37], v[12:13], v[36:37]
	v_pk_mul_f32 v[38:39], v[14:15], v[38:39]
	global_store_dwordx4 v[20:21], v[24:27], off offset:-3072
	global_store_dwordx4 v[20:21], v[28:31], off offset:-2048
	global_store_dwordx4 v[20:21], v[32:35], off offset:-1024
	global_store_dwordx4 v[20:21], v[36:39], off
	v_lshl_add_u64 v[20:21], v[20:21], 0, s[8:9]
	s_add_i32 s88, s88, s94
	s_cmp_lt_i32 s88, s28
	s_cbranch_scc0 .Lfn_done
	global_load_dwordx2 v[104:105], v[18:19], off
	global_load_dwordx2 v[106:107], v[18:19], off offset:512
	global_load_dwordx2 v[108:109], v[18:19], off offset:1024
	global_load_dwordx2 v[110:111], v[18:19], off offset:1536
	global_load_dwordx4 v[112:115], v17, s[12:13] offset:48
	global_load_dwordx4 v[116:119], v17, s[12:13] offset:32
	global_load_dwordx4 v[120:123], v17, s[12:13] offset:16
	global_load_dwordx4 v[124:127], v17, s[12:13]
	s_add_i32 s22, s22, s94
	s_cmp_lt_i32 s22, s28
	s_cselect_b32 s24, s6, 0
	s_cselect_b32 s25, s7, 0
	s_cselect_b32 s26, s4, 0
	s_cselect_b32 s27, s5, 0
	v_lshl_add_u64 v[18:19], v[18:19], 0, s[24:25]
	s_add_u32 s12, s12, s26
	s_addc_u32 s13, s13, s27
	s_waitcnt vmcnt(20)
	v_pk_add_f32 v[74:75], v[78:79], v[74:75]
	v_pk_add_f32 v[72:73], v[76:77], v[72:73]
	v_pk_add_f32 v[70:71], v[74:75], v[70:71]
	v_pk_add_f32 v[68:69], v[72:73], v[68:69]
	v_pk_add_f32 v[66:67], v[70:71], v[66:67]
	v_pk_add_f32 v[64:65], v[68:69], v[64:65]
	v_mov_b32_e32 v69, v66
	v_mov_b32_e32 v68, v65
	v_mov_b32_e32 v65, v67
	v_pk_add_f32 v[64:65], v[68:69], v[64:65]
	v_lshlrev_b32_e32 v128, 16, v56
	v_and_b32_e32 v129, 0xffff0000, v56
	v_lshlrev_b32_e32 v132, 16, v58
	v_and_b32_e32 v133, 0xffff0000, v58
	v_lshlrev_b32_e32 v136, 16, v60
	v_and_b32_e32 v137, 0xffff0000, v60
	v_lshlrev_b32_e32 v140, 16, v62
	v_and_b32_e32 v141, 0xffff0000, v62
	v_add_f32_e32 v23, v64, v65
	v_fmamk_f32 v23, v23, 0x3a800000, v22
	v_mul_f32_e32 v50, 0x4b800000, v23
	v_cmp_gt_f32_e32 vcc, s10, v23
	v_lshlrev_b32_e32 v130, 16, v57
	v_and_b32_e32 v131, 0xffff0000, v57
	v_lshlrev_b32_e32 v134, 16, v59
	v_and_b32_e32 v135, 0xffff0000, v59
	v_cndmask_b32_e32 v23, v23, v50, vcc
	v_rsq_f32_e32 v23, v23
	v_lshlrev_b32_e32 v138, 16, v61
	v_and_b32_e32 v139, 0xffff0000, v61
	v_lshlrev_b32_e32 v142, 16, v63
	v_and_b32_e32 v143, 0xffff0000, v63
	v_mul_f32_e32 v50, 0x45800000, v23
	s_nop 1
	v_cndmask_b32_e32 v50, v23, v50, vcc
	v_pk_mul_f32 v[24:25], v[50:51], v[128:129] op_sel_hi:[0,1]
	v_pk_mul_f32 v[26:27], v[50:51], v[130:131] op_sel_hi:[0,1]
	v_pk_mul_f32 v[28:29], v[50:51], v[132:133] op_sel_hi:[0,1]
	v_pk_mul_f32 v[30:31], v[50:51], v[134:135] op_sel_hi:[0,1]
	v_pk_mul_f32 v[32:33], v[50:51], v[136:137] op_sel_hi:[0,1]
	v_pk_mul_f32 v[34:35], v[50:51], v[138:139] op_sel_hi:[0,1]
	v_pk_mul_f32 v[36:37], v[50:51], v[140:141] op_sel_hi:[0,1]
	v_pk_mul_f32 v[38:39], v[50:51], v[142:143] op_sel_hi:[0,1]
	v_pk_mul_f32 v[24:25], v[0:1], v[24:25]
	v_pk_mul_f32 v[26:27], v[2:3], v[26:27]
	v_pk_mul_f32 v[28:29], v[4:5], v[28:29]
	v_pk_mul_f32 v[30:31], v[6:7], v[30:31]
	v_pk_mul_f32 v[32:33], v[8:9], v[32:33]
	v_pk_mul_f32 v[34:35], v[10:11], v[34:35]
	v_pk_mul_f32 v[36:37], v[12:13], v[36:37]
	v_pk_mul_f32 v[38:39], v[14:15], v[38:39]
	global_store_dwordx4 v[20:21], v[24:27], off offset:-3072
	global_store_dwordx4 v[20:21], v[28:31], off offset:-2048
	global_store_dwordx4 v[20:21], v[32:35], off offset:-1024
	global_store_dwordx4 v[20:21], v[36:39], off
	v_lshl_add_u64 v[20:21], v[20:21], 0, s[8:9]
	s_add_i32 s88, s88, s94
	s_cmp_lt_i32 s88, s28
	s_cbranch_scc1 .Lfn_loop
